# NSA: second gate of the compressed-branch output and the window-branch finalisation loads requested ahead of the preceding stores (counted waits), on top of the selected-branch finalisation change
# baseline (speedup 1.0000x reference)
.LBB0_1094:
	v_lshl_add_u32 v180, v79, 1, v79
	v_lshlrev_b32_e32 v0, 1, v80
	v_lshl_add_u64 v[50:51], s[18:19], 0, v[0:1]
	v_lshlrev_b32_e32 v0, 1, v180
	v_lshl_add_u64 v[52:53], v[64:65], 0, v[0:1]
	s_movk_i32 s10, 0x4000
	v_add_co_u32_e32 v52, vcc, s10, v52
	s_waitcnt vmcnt(0) lgkmcnt(0)
	s_barrier
	v_mov_b32_e32 v171, v1
	s_nop 0
	v_addc_co_u32_e32 v53, vcc, 0, v53, vcc
	global_load_ushort v52, v[52:53], off offset:1280
	v_lshl_add_u64 v[50:51], v[50:51], 0, v[170:171]
	s_movk_i32 s13, 0x600
	v_mad_i64_i32 v[168:169], s[6:7], v77, s13, v[50:51]
	s_and_b32 s6, s79, 0x3fffffc0
	s_lshl_b32 s6, s6, 2
	s_add_i32 s12, s6, 0
	v_mad_i64_i32 v[166:167], s[6:7], v76, s13, v[50:51]
	v_cmp_eq_u32_e64 s[30:31], 0, v74
	s_mov_b32 s11, 0
	s_add_i32 s12, s12, 0x20000
	s_waitcnt vmcnt(0)
	v_lshlrev_b32_e32 v52, 16, v52
	v_mul_f32_e32 v52, 0xbfb8aa3b, v52
	v_exp_f32_e32 v54, v52
	v_lshl_add_u64 v[52:53], v[62:63], 0, v[0:1]
	v_add_co_u32_e32 v52, vcc, s10, v52
	v_add_f32_e32 v0, 1.0, v54
	v_rcp_f32_e32 v0, v0
	v_addc_co_u32_e32 v53, vcc, 0, v53, vcc
	global_load_ushort v56, v[52:53], off offset:1280
	v_cmp_eq_u32_e32 vcc, s25, v74
	v_pk_mul_f32 v[48:49], v[48:49], v[0:1] op_sel_hi:[1,0]
	v_pk_mul_f32 v[46:47], v[46:47], v[0:1] op_sel_hi:[1,0]
	v_pk_mul_f32 v[36:37], v[36:37], v[0:1] op_sel_hi:[1,0]
	v_pk_mul_f32 v[34:35], v[34:35], v[0:1] op_sel_hi:[1,0]
	v_pk_mul_f32 v[44:45], v[44:45], v[0:1] op_sel_hi:[1,0]
	v_pk_mul_f32 v[42:43], v[42:43], v[0:1] op_sel_hi:[1,0]
	v_pk_mul_f32 v[40:41], v[40:41], v[0:1] op_sel_hi:[1,0]
	v_pk_mul_f32 v[38:39], v[38:39], v[0:1] op_sel_hi:[1,0]
	v_cvt_pk_bf16_f32 v46, v46, v47
	v_cvt_pk_bf16_f32 v47, v48, v49
	v_cvt_pk_bf16_f32 v34, v34, v35
	v_cvt_pk_bf16_f32 v35, v36, v37
	v_cvt_pk_bf16_f32 v36, v42, v43
	v_cvt_pk_bf16_f32 v37, v44, v45
	v_cvt_pk_bf16_f32 v38, v38, v39
	v_cvt_pk_bf16_f32 v39, v40, v41
	global_store_dwordx2 v[168:169], v[46:47], off
	global_store_dwordx2 v[168:169], v[34:35], off offset:32
	global_store_dwordx2 v[168:169], v[36:37], off offset:64
	global_store_dwordx2 v[168:169], v[38:39], off offset:96
	v_lshlrev_b64 v[34:35], v74, -1
	v_not_b32_e32 v0, v34
	v_not_b32_e32 v35, v35
	v_or_b32_e32 v37, 64, v74
	v_or_b32_e32 v38, 0x80, v74
	s_add_i32 s10, s34, 0
	v_cmp_ge_u32_e64 s[34:35], s25, v74
	s_or_b64 s[36:37], s[30:31], vcc
	v_cmp_ge_u32_e64 s[38:39], s25, v37
	v_cmp_eq_u32_e64 s[40:41], s25, v37
	v_cmp_ge_u32_e64 s[42:43], s25, v38
	v_cmp_eq_u32_e64 s[44:45], s25, v38
	s_waitcnt vmcnt(4)
	v_lshlrev_b32_e32 v34, 16, v56
	v_mul_f32_e32 v34, 0xbfb8aa3b, v34
	v_exp_f32_e32 v34, v34
	s_nop 0
	v_add_f32_e32 v34, 1.0, v34
	v_rcp_f32_e32 v34, v34
	s_nop 0
	v_pk_mul_f32 v[20:21], v[20:21], v[34:35] op_sel_hi:[1,0]
	v_pk_mul_f32 v[18:19], v[18:19], v[34:35] op_sel_hi:[1,0]
	v_pk_mul_f32 v[24:25], v[24:25], v[34:35] op_sel_hi:[1,0]
	v_pk_mul_f32 v[22:23], v[22:23], v[34:35] op_sel_hi:[1,0]
	v_pk_mul_f32 v[32:33], v[32:33], v[34:35] op_sel_hi:[1,0]
	v_pk_mul_f32 v[30:31], v[30:31], v[34:35] op_sel_hi:[1,0]
	v_pk_mul_f32 v[28:29], v[28:29], v[34:35] op_sel_hi:[1,0]
	v_pk_mul_f32 v[26:27], v[26:27], v[34:35] op_sel_hi:[1,0]
	v_cvt_pk_bf16_f32 v18, v18, v19
	v_cvt_pk_bf16_f32 v19, v20, v21
	v_cvt_pk_bf16_f32 v20, v22, v23
	v_cvt_pk_bf16_f32 v21, v24, v25
	v_cvt_pk_bf16_f32 v22, v30, v31
	v_cvt_pk_bf16_f32 v23, v32, v33
	v_cvt_pk_bf16_f32 v24, v26, v27
	v_cvt_pk_bf16_f32 v25, v28, v29
	global_store_dwordx2 v[166:167], v[18:19], off
	global_store_dwordx2 v[166:167], v[20:21], off offset:32
	global_store_dwordx2 v[166:167], v[22:23], off offset:64
	global_store_dwordx2 v[166:167], v[24:25], off offset:96
	s_waitcnt lgkmcnt(0)
	v_or_b32_e32 v18, 0xc0, v74
	v_cmp_ge_u32_e64 s[46:47], s25, v18
	v_cmp_eq_u32_e64 s[48:49], s25, v18
	s_branch .LBB0_1096

.LBB0_1254:
	s_waitcnt vmcnt(3)
	v_add_co_u32_e32 v6, vcc, 0x4000, v100
	s_waitcnt vmcnt(0) lgkmcnt(0)
	s_barrier
	global_load_dwordx2 v[2:3], v[168:169], off
	global_load_dwordx2 v[4:5], v[168:169], off offset:32
	v_addc_co_u32_e32 v7, vcc, 0, v101, vcc
	global_load_dwordx2 v[8:9], v[168:169], off offset:64
	global_load_ushort v0, v[6:7], off offset:1284
	s_nop 0
	global_load_dwordx2 v[6:7], v[168:169], off offset:96
	s_waitcnt vmcnt(7)
	ds_bpermute_b32 v11, v213, v109
	ds_bpermute_b32 v10, v213, v108
	s_movk_i32 s6, 0x4000
	s_waitcnt vmcnt(6)
	v_add_co_u32_e32 v14, vcc, s6, v102
	global_load_dwordx2 v[16:17], v[166:167], off
	global_load_dwordx2 v[18:19], v[166:167], off offset:32
	global_load_dwordx2 v[20:21], v[166:167], off offset:64
	s_waitcnt lgkmcnt(0)
	v_pk_add_f32 v[10:11], v[108:109], v[10:11]
	ds_bpermute_b32 v13, v214, v11
	ds_bpermute_b32 v12, v214, v10
	v_addc_co_u32_e32 v15, vcc, 0, v103, vcc
	global_load_ushort v84, v[14:15], off offset:1284
	global_load_dwordx2 v[86:87], v[166:167], off offset:96
	s_waitcnt lgkmcnt(0)
	v_pk_add_f32 v[10:11], v[10:11], v[12:13]
	s_waitcnt vmcnt(9)
	v_lshlrev_b32_e32 v12, 16, v2
	v_and_b32_e32 v13, 0xffff0000, v2
	v_lshlrev_b32_e32 v2, 16, v3
	v_and_b32_e32 v3, 0xffff0000, v3
	s_waitcnt vmcnt(6)
	v_lshlrev_b32_e32 v0, 16, v0
	v_mul_f32_e32 v0, 0xbfb8aa3b, v0
	v_exp_f32_e32 v0, v0
	v_lshlrev_b32_e32 v22, 16, v4
	v_and_b32_e32 v23, 0xffff0000, v4
	v_lshlrev_b32_e32 v4, 16, v5
	v_add_f32_e32 v0, 1.0, v0
	v_rcp_f32_e32 v0, v0
	v_and_b32_e32 v5, 0xffff0000, v5
	v_lshlrev_b32_e32 v24, 16, v8
	v_and_b32_e32 v25, 0xffff0000, v8
	v_div_scale_f32 v28, s[6:7], v11, v11, v0
	v_rcp_f32_e32 v29, v28
	v_div_scale_f32 v30, vcc, v0, v11, v0
	v_lshlrev_b32_e32 v8, 16, v9
	v_fma_f32 v31, -v28, v29, 1.0
	v_fmac_f32_e32 v29, v31, v29
	v_mul_f32_e32 v31, v30, v29
	v_fma_f32 v32, -v28, v31, v30
	v_fmac_f32_e32 v31, v32, v29
	v_fma_f32 v28, -v28, v31, v30
	v_div_fmas_f32 v28, v28, v29, v31
	v_div_fixup_f32 v0, v28, v11, v0
	v_cmp_lt_f32_e32 vcc, 0, v11
	v_and_b32_e32 v9, 0xffff0000, v9
	s_waitcnt vmcnt(5)
	v_lshlrev_b32_e32 v26, 16, v6
	v_cndmask_b32_e32 v0, 0, v0, vcc
	v_and_b32_e32 v27, 0xffff0000, v6
	v_lshlrev_b32_e32 v6, 16, v7
	v_and_b32_e32 v7, 0xffff0000, v7
	v_pk_fma_f32 v[12:13], v[36:37], v[0:1], v[12:13] op_sel_hi:[1,0,1]
	v_pk_fma_f32 v[2:3], v[38:39], v[0:1], v[2:3] op_sel_hi:[1,0,1]
	v_pk_fma_f32 v[22:23], v[40:41], v[0:1], v[22:23] op_sel_hi:[1,0,1]
	v_pk_fma_f32 v[4:5], v[42:43], v[0:1], v[4:5] op_sel_hi:[1,0,1]
	v_pk_fma_f32 v[24:25], v[44:45], v[0:1], v[24:25] op_sel_hi:[1,0,1]
	v_pk_fma_f32 v[8:9], v[46:47], v[0:1], v[8:9] op_sel_hi:[1,0,1]
	v_pk_fma_f32 v[26:27], v[48:49], v[0:1], v[26:27] op_sel_hi:[1,0,1]
	v_pk_fma_f32 v[6:7], v[50:51], v[0:1], v[6:7] op_sel_hi:[1,0,1]
	v_cvt_pk_bf16_f32 v12, v12, v13
	v_cvt_pk_bf16_f32 v13, v2, v3
	v_cvt_pk_bf16_f32 v2, v22, v23
	v_cvt_pk_bf16_f32 v3, v4, v5
	v_cvt_pk_bf16_f32 v4, v24, v25
	v_cvt_pk_bf16_f32 v5, v8, v9
	v_cvt_pk_bf16_f32 v8, v26, v27
	v_cvt_pk_bf16_f32 v9, v6, v7
	global_store_dwordx2 v[168:169], v[12:13], off
	global_store_dwordx2 v[168:169], v[2:3], off offset:32
	global_store_dwordx2 v[168:169], v[4:5], off offset:64
	global_store_dwordx2 v[168:169], v[8:9], off offset:96
	s_waitcnt vmcnt(6)
	v_lshlrev_b32_e32 v14, 16, v20
	v_and_b32_e32 v15, 0xffff0000, v20
	v_lshlrev_b32_e32 v4, 16, v16
	v_and_b32_e32 v5, 0xffff0000, v16
	v_lshlrev_b32_e32 v6, 16, v17
	v_and_b32_e32 v7, 0xffff0000, v17
	v_lshlrev_b32_e32 v16, 16, v21
	v_and_b32_e32 v17, 0xffff0000, v21
	v_lshlrev_b32_e32 v8, 16, v18
	v_and_b32_e32 v9, 0xffff0000, v18
	v_lshlrev_b32_e32 v12, 16, v19
	v_and_b32_e32 v13, 0xffff0000, v19
	s_waitcnt vmcnt(5)
	v_lshlrev_b32_e32 v0, 16, v84
	v_mul_f32_e32 v0, 0xbfb8aa3b, v0
	v_exp_f32_e32 v0, v0
	s_waitcnt vmcnt(4)
	v_lshlrev_b32_e32 v18, 16, v86
	v_and_b32_e32 v19, 0xffff0000, v86
	v_lshlrev_b32_e32 v2, 16, v87
	v_add_f32_e32 v0, 1.0, v0
	v_rcp_f32_e32 v0, v0
	v_and_b32_e32 v3, 0xffff0000, v87
	v_div_scale_f32 v11, s[6:7], v10, v10, v0
	v_rcp_f32_e32 v20, v11
	v_div_scale_f32 v21, vcc, v0, v10, v0
	v_fma_f32 v22, -v11, v20, 1.0
	v_fmac_f32_e32 v20, v22, v20
	v_mul_f32_e32 v22, v21, v20
	v_fma_f32 v23, -v11, v22, v21
	v_fmac_f32_e32 v22, v23, v20
	v_fma_f32 v11, -v11, v22, v21
	v_div_fmas_f32 v11, v11, v20, v22
	v_div_fixup_f32 v0, v11, v10, v0
	v_cmp_lt_f32_e32 vcc, 0, v10
	s_nop 1
	v_cndmask_b32_e32 v0, 0, v0, vcc
	v_pk_fma_f32 v[4:5], v[68:69], v[0:1], v[4:5] op_sel_hi:[1,0,1]
	v_pk_fma_f32 v[6:7], v[70:71], v[0:1], v[6:7] op_sel_hi:[1,0,1]
	v_pk_fma_f32 v[8:9], v[72:73], v[0:1], v[8:9] op_sel_hi:[1,0,1]
	v_pk_fma_f32 v[10:11], v[74:75], v[0:1], v[12:13] op_sel_hi:[1,0,1]
	v_pk_fma_f32 v[12:13], v[76:77], v[0:1], v[14:15] op_sel_hi:[1,0,1]
	v_pk_fma_f32 v[14:15], v[78:79], v[0:1], v[16:17] op_sel_hi:[1,0,1]
	v_pk_fma_f32 v[16:17], v[80:81], v[0:1], v[18:19] op_sel_hi:[1,0,1]
	v_pk_fma_f32 v[2:3], v[82:83], v[0:1], v[2:3] op_sel_hi:[1,0,1]
	v_cvt_pk_bf16_f32 v4, v4, v5
	v_cvt_pk_bf16_f32 v5, v6, v7
	v_cvt_pk_bf16_f32 v6, v8, v9
	v_cvt_pk_bf16_f32 v7, v10, v11
	v_cvt_pk_bf16_f32 v8, v12, v13
	v_cvt_pk_bf16_f32 v9, v14, v15
	v_cvt_pk_bf16_f32 v10, v16, v17
	v_cvt_pk_bf16_f32 v11, v2, v3
	global_store_dwordx2 v[166:167], v[4:5], off
	global_store_dwordx2 v[166:167], v[6:7], off offset:32
	global_store_dwordx2 v[166:167], v[8:9], off offset:64
	global_store_dwordx2 v[166:167], v[10:11], off offset:96
